# stack (p2swap, attn ladder, attn gate prefetch, permlane butterflies) + P7 epilogue: lambda-constant load issued with the epilogue-start loads (one less exposed round trip per unit)
# speedup vs baseline: 1.0114x; 1.0114x over previous
.LBB0_863:
	v_mov_b32_e32 v154, v1
	v_mov_b32_e32 v229, v220
	s_lshl_b32 s14, s21, 6
	v_lshlrev_b32_e32 v90, 2, v229
	v_add_u32_e32 v230, s34, v90
	v_and_b32_e32 v90, -8, v90
	v_lshlrev_b32_e32 v91, 5, v229
	v_add_u32_e32 v90, s34, v90
	v_and_b32_e32 v91, 32, v91
	v_add_u32_e32 v156, s14, v230
	v_add_u32_e32 v228, s14, v90
	v_add_u32_e32 v91, v91, v154
	v_bfe_u32 v226, v90, 5, 1
	v_lshlrev_b32_e32 v90, 1, v90
	s_add_i32 s14, s20, s28
	v_and_b32_e32 v225, 48, v90
	v_add_u32_e32 v90, s14, v91
	v_lshrrev_b32_e32 v92, 2, v90
	v_lshrrev_b32_e32 v93, 3, v90
	v_lshlrev_b32_e32 v95, 6, v90
	v_lshlrev_b32_e32 v90, 2, v90
	v_ashrrev_i32_e32 v227, 6, v228
	v_and_b32_e32 v92, 0x3ffe0, v92
	v_and_or_b32 v93, v93, 14, v226
	v_and_b32_e32 v95, 0x3c0, v95
	v_and_b32_e32 v90, 32, v90
	v_add_u32_e32 v94, 16, v91
	v_add_lshl_u32 v92, v92, v227, 14
	v_lshlrev_b32_e32 v93, 10, v93
	v_bitop3_b32 v90, v95, v90, v225 bitop3:0x36
	v_or3_b32 v90, v90, v93, v92
	v_add_u32_e32 v92, s14, v94
	v_lshrrev_b32_e32 v93, 2, v92
	v_lshrrev_b32_e32 v95, 3, v92
	v_lshlrev_b32_e32 v96, 6, v92
	v_lshlrev_b32_e32 v92, 2, v92
	v_and_b32_e32 v93, 0x3ffe0, v93
	v_and_or_b32 v95, v95, 14, v226
	v_and_b32_e32 v96, 0x3c0, v96
	v_and_b32_e32 v92, 32, v92
	v_add_lshl_u32 v93, v93, v227, 14
	v_lshlrev_b32_e32 v95, 10, v95
	v_bitop3_b32 v92, v96, v92, v225 bitop3:0x36
	s_addk_i32 s14, 0x80
	v_or3_b32 v92, v92, v95, v93
	global_load_dwordx4 v[138:141], v90, s[36:37]
	global_load_dwordx4 v[134:137], v92, s[36:37]
	v_add_u32_e32 v90, s14, v91
	v_lshrrev_b32_e32 v91, 2, v90
	v_lshrrev_b32_e32 v92, 3, v90
	v_lshlrev_b32_e32 v93, 6, v90
	v_lshlrev_b32_e32 v90, 2, v90
	v_ashrrev_i32_e32 v157, 31, v156
	v_and_b32_e32 v91, 0x3ffe0, v91
	v_and_or_b32 v92, v92, 14, v226
	v_and_b32_e32 v93, 0x3c0, v93
	v_and_b32_e32 v90, 32, v90
	v_lshlrev_b64 v[150:151], 2, v[156:157]
	v_add_lshl_u32 v91, v91, v227, 14
	v_lshlrev_b32_e32 v92, 10, v92
	v_bitop3_b32 v90, v93, v90, v225 bitop3:0x36
	v_lshl_add_u64 v[162:163], s[44:45], 0, v[150:151]
	v_or3_b32 v90, v90, v92, v91
	global_load_dwordx4 v[158:161], v[162:163], off
	v_add_u32_e32 v94, s14, v94
	global_load_dwordx4 v[90:93], v90, s[36:37]
	v_lshl_add_u64 v[164:165], s[42:43], 0, v[150:151]
	v_lshrrev_b32_e32 v95, 2, v94
	v_lshrrev_b32_e32 v96, 3, v94
	v_lshlrev_b32_e32 v97, 6, v94
	v_lshlrev_b32_e32 v94, 2, v94
	global_load_dwordx4 v[168:171], v[164:165], off
	v_and_b32_e32 v95, 0x3ffe0, v95
	v_and_or_b32 v96, v96, 14, v226
	v_and_b32_e32 v97, 0x3c0, v97
	v_and_b32_e32 v94, 32, v94
	v_add_lshl_u32 v95, v95, v227, 14
	v_lshlrev_b32_e32 v96, 10, v96
	v_bitop3_b32 v94, v97, v94, v225 bitop3:0x36
	v_or3_b32 v94, v94, v96, v95
	global_load_dwordx4 v[94:97], v94, s[36:37]
	v_readlane_b32 s14, v255, 8
	v_readlane_b32 s15, v255, 9
	s_nop 1
	v_lshl_add_u64 v[166:167], s[14:15], 0, v[150:151]
	global_load_dwordx4 v[130:133], v[166:167], off
	s_waitcnt vmcnt(0)
	v_mov_b32_e32 v186, v140
	v_mov_b32_e32 v187, v141
	v_mov_b32_e32 v190, v136
	v_mov_b32_e32 v191, v137
	v_permlane16_swap_b32_e32 v138, v186
	v_permlane16_swap_b32_e32 v139, v187
	v_permlane16_swap_b32_e32 v134, v190
	v_permlane16_swap_b32_e32 v135, v191
	v_mul_f32_e32 v178, 0xbfb8aa3b, v158
	v_mul_f32_e32 v180, 0xbfb8aa3b, v160
	v_mov_b32_e32 v212, v92
	v_fmamk_f32 v92, v142, 0xbfb8aa3b, v178
	v_fmamk_f32 v140, v144, 0xbfb8aa3b, v180
	v_mov_b32_e32 v214, v93
	v_exp_f32_e32 v93, v92
	v_exp_f32_e32 v141, v140
	v_mul_f32_e32 v179, 0xbfb8aa3b, v168
	v_fmamk_f32 v92, v146, 0xbfb8aa3b, v179
	v_mul_f32_e32 v146, 0xbfb8aa3b, v169
	v_mul_f32_e32 v181, 0xbfb8aa3b, v170
	v_mul_f32_e32 v184, 0xbfb8aa3b, v171
	v_add_f32_e32 v136, 1.0, v93
	v_fmamk_f32 v93, v147, 0xbfb8aa3b, v146
	v_fmamk_f32 v140, v148, 0xbfb8aa3b, v181
	v_add_f32_e32 v144, 1.0, v141
	v_fmamk_f32 v141, v149, 0xbfb8aa3b, v184
	v_exp_f32_e32 v92, v92
	v_exp_f32_e32 v93, v93
	v_mul_f32_e32 v147, 0xbfb8aa3b, v159
	v_exp_f32_e32 v140, v140
	v_exp_f32_e32 v141, v141
	v_mul_f32_e32 v185, 0xbfb8aa3b, v161
	v_mov_b32_e32 v213, v96
	v_fmamk_f32 v96, v143, 0xbfb8aa3b, v147
	v_fmamk_f32 v142, v145, 0xbfb8aa3b, v185
	v_mov_b32_e32 v215, v97
	v_exp_f32_e32 v97, v96
	v_exp_f32_e32 v143, v142
	v_pk_add_f32 v[92:93], v[92:93], 1.0 op_sel_hi:[1,0]
	v_pk_add_f32 v[140:141], v[140:141], 1.0 op_sel_hi:[1,0]
	v_mul_f32_e32 v96, v92, v136
	v_mul_f32_e32 v142, v140, v144
	v_rcp_f32_e32 v96, v96
	v_add_f32_e32 v137, 1.0, v97
	v_rcp_f32_e32 v142, v142
	v_add_f32_e32 v145, 1.0, v143
	v_mul_f32_e32 v97, v93, v137
	v_mul_f32_e32 v143, v141, v145
	v_rcp_f32_e32 v97, v97
	v_rcp_f32_e32 v143, v143
	v_mul_f32_e32 v136, v136, v96
	v_mul_f32_e32 v144, v144, v142
	v_pk_mul_f32 v[92:93], v[92:93], v[96:97]
	v_pk_mul_f32 v[140:141], v[140:141], v[142:143]
	v_permlane16_swap_b32_e32 v90, v212
	v_permlane16_swap_b32_e32 v91, v214
	v_permlane16_swap_b32_e32 v94, v213
	v_permlane16_swap_b32_e32 v95, v215
	s_waitcnt vmcnt(0)
	v_mul_f32_e32 v136, v130, v136
	v_mul_f32_e32 v144, v132, v144
	v_exp_f32_e32 v158, v136
	v_mul_f32_e32 v136, v137, v97
	v_exp_f32_e32 v160, v144
	v_mul_f32_e32 v144, v145, v143
	v_mul_f32_e32 v136, v131, v136
	v_mul_f32_e32 v144, v133, v144
	v_exp_f32_e32 v159, v136
	v_exp_f32_e32 v161, v144
	v_fma_f32 v136, -v158, v158, 1.0
	v_fma_f32 v144, -v160, v160, 1.0
	v_fma_f32 v137, -v159, v159, 1.0
	v_fma_f32 v145, -v161, v161, 1.0
	v_sqrt_f32_e32 v136, v136
	v_sqrt_f32_e32 v137, v137
	v_sqrt_f32_e32 v144, v144
	v_sqrt_f32_e32 v145, v145
	v_pk_mul_f32 v[96:97], v[92:93], v[136:137]
	v_pk_mul_f32 v[136:137], v[140:141], v[144:145]
	v_fmamk_f32 v93, v122, 0xbfb8aa3b, v178
	v_fmamk_f32 v124, v124, 0xbfb8aa3b, v180
	v_exp_f32_e32 v122, v93
	v_exp_f32_e32 v124, v124
	v_fmamk_f32 v128, v128, 0xbfb8aa3b, v181
	v_fmamk_f32 v129, v129, 0xbfb8aa3b, v184
	v_fmamk_f32 v92, v126, 0xbfb8aa3b, v179
	v_fmamk_f32 v93, v127, 0xbfb8aa3b, v146
	v_exp_f32_e32 v128, v128
	v_exp_f32_e32 v129, v129
	v_exp_f32_e32 v92, v92
	v_exp_f32_e32 v93, v93
	v_add_f32_e32 v140, 1.0, v122
	v_fmamk_f32 v122, v123, 0xbfb8aa3b, v147
	v_add_f32_e32 v142, 1.0, v124
	v_fmamk_f32 v124, v125, 0xbfb8aa3b, v185
	v_exp_f32_e32 v127, v122
	v_exp_f32_e32 v143, v124
	v_pk_add_f32 v[124:125], v[128:129], 1.0 op_sel_hi:[1,0]
	v_pk_add_f32 v[122:123], v[92:93], 1.0 op_sel_hi:[1,0]
	v_mul_f32_e32 v128, v124, v142
	v_mul_f32_e32 v92, v122, v140
	v_add_f32_e32 v93, 1.0, v127
	v_rcp_f32_e32 v128, v128
	v_add_f32_e32 v143, 1.0, v143
	v_rcp_f32_e32 v126, v92
	v_mul_f32_e32 v92, v123, v93
	v_mul_f32_e32 v129, v125, v143
	v_rcp_f32_e32 v127, v92
	v_rcp_f32_e32 v129, v129
	v_mul_f32_e32 v142, v142, v128
	v_mul_f32_e32 v142, v132, v142
	v_mul_f32_e32 v92, v140, v126
	v_mul_f32_e32 v93, v93, v127
	v_exp_f32_e32 v148, v142
	v_mul_f32_e32 v142, v143, v129
	v_mul_f32_e32 v92, v130, v92
	v_mul_f32_e32 v93, v131, v93
	v_mul_f32_e32 v142, v133, v142
	v_exp_f32_e32 v92, v92
	v_exp_f32_e32 v93, v93
	v_exp_f32_e32 v149, v142
	v_fma_f32 v142, -v148, v148, 1.0
	v_fma_f32 v140, -v92, v92, 1.0
	v_fma_f32 v141, -v93, v93, 1.0
	v_fma_f32 v143, -v149, v149, 1.0
	v_sqrt_f32_e32 v140, v140
	v_sqrt_f32_e32 v141, v141
	v_sqrt_f32_e32 v142, v142
	v_sqrt_f32_e32 v143, v143
	v_pk_mul_f32 v[122:123], v[122:123], v[126:127]
	v_pk_mul_f32 v[124:125], v[124:125], v[128:129]
	v_pk_mul_f32 v[168:169], v[122:123], v[140:141]
	v_pk_mul_f32 v[170:171], v[124:125], v[142:143]
	v_fmamk_f32 v74, v74, 0xbfb8aa3b, v178
	v_fmamk_f32 v76, v76, 0xbfb8aa3b, v180
	v_exp_f32_e32 v74, v74
	v_exp_f32_e32 v76, v76
	v_fmamk_f32 v86, v86, 0xbfb8aa3b, v179
	v_fmamk_f32 v87, v87, 0xbfb8aa3b, v146
	v_fmamk_f32 v88, v88, 0xbfb8aa3b, v181
	v_fmamk_f32 v89, v89, 0xbfb8aa3b, v184
	v_exp_f32_e32 v86, v86
	v_exp_f32_e32 v87, v87
	v_exp_f32_e32 v88, v88
	v_exp_f32_e32 v89, v89
	v_add_f32_e32 v122, 1.0, v74
	v_fmamk_f32 v74, v75, 0xbfb8aa3b, v147
	v_add_f32_e32 v124, 1.0, v76
	v_fmamk_f32 v76, v77, 0xbfb8aa3b, v185
	v_exp_f32_e32 v123, v74
	v_exp_f32_e32 v125, v76
	v_pk_add_f32 v[74:75], v[86:87], 1.0 op_sel_hi:[1,0]
	v_pk_add_f32 v[76:77], v[88:89], 1.0 op_sel_hi:[1,0]
	v_mul_f32_e32 v86, v74, v122
	v_mul_f32_e32 v88, v76, v124
	v_rcp_f32_e32 v86, v86
	v_add_f32_e32 v123, 1.0, v123
	v_rcp_f32_e32 v88, v88
	v_add_f32_e32 v125, 1.0, v125
	v_mul_f32_e32 v87, v75, v123
	v_mul_f32_e32 v89, v77, v125
	v_rcp_f32_e32 v87, v87
	v_rcp_f32_e32 v89, v89
	v_mul_f32_e32 v122, v122, v86
	v_mul_f32_e32 v124, v124, v88
	v_mul_f32_e32 v122, v130, v122
	v_mul_f32_e32 v124, v132, v124
	v_exp_f32_e32 v172, v122
	v_mul_f32_e32 v122, v123, v87
	v_exp_f32_e32 v182, v124
	v_mul_f32_e32 v124, v125, v89
	v_mul_f32_e32 v122, v131, v122
	v_mul_f32_e32 v124, v133, v124
	v_exp_f32_e32 v173, v122
	v_exp_f32_e32 v183, v124
	v_fma_f32 v122, -v172, v172, 1.0
	v_fma_f32 v124, -v182, v182, 1.0
	v_fma_f32 v123, -v173, v173, 1.0
	v_fma_f32 v125, -v183, v183, 1.0
	v_sqrt_f32_e32 v122, v122
	v_sqrt_f32_e32 v123, v123
	v_sqrt_f32_e32 v124, v124
	v_sqrt_f32_e32 v125, v125
	v_pk_mul_f32 v[74:75], v[74:75], v[86:87]
	v_pk_mul_f32 v[76:77], v[76:77], v[88:89]
	v_pk_mul_f32 v[174:175], v[74:75], v[122:123]
	v_pk_mul_f32 v[176:177], v[76:77], v[124:125]
	v_fmac_f32_e32 v179, 0xbfb8aa3b, v70
	v_fmac_f32_e32 v178, 0xbfb8aa3b, v50
	v_fmac_f32_e32 v146, 0xbfb8aa3b, v71
	v_fmac_f32_e32 v181, 0xbfb8aa3b, v72
	v_fmac_f32_e32 v180, 0xbfb8aa3b, v52
	v_fmac_f32_e32 v184, 0xbfb8aa3b, v73
	v_exp_f32_e32 v50, v178
	v_exp_f32_e32 v70, v179
	v_exp_f32_e32 v71, v146
	v_exp_f32_e32 v52, v180
	v_exp_f32_e32 v72, v181
	v_exp_f32_e32 v73, v184
	v_fmac_f32_e32 v147, 0xbfb8aa3b, v51
	v_fmac_f32_e32 v185, 0xbfb8aa3b, v53
	v_exp_f32_e32 v75, v147
	v_exp_f32_e32 v77, v185
	v_add_f32_e32 v74, 1.0, v50
	v_pk_add_f32 v[50:51], v[70:71], 1.0 op_sel_hi:[1,0]
	v_add_f32_e32 v76, 1.0, v52
	v_pk_add_f32 v[52:53], v[72:73], 1.0 op_sel_hi:[1,0]
	v_mul_f32_e32 v70, v50, v74
	v_mul_f32_e32 v72, v52, v76
	v_rcp_f32_e32 v70, v70
	v_add_f32_e32 v75, 1.0, v75
	v_rcp_f32_e32 v72, v72
	v_add_f32_e32 v77, 1.0, v77
	v_mul_f32_e32 v71, v51, v75
	v_mul_f32_e32 v73, v53, v77
	v_rcp_f32_e32 v71, v71
	v_rcp_f32_e32 v73, v73
	v_mul_f32_e32 v74, v74, v70
	v_mul_f32_e32 v76, v76, v72
	v_mul_f32_e32 v74, v130, v74
	v_mul_f32_e32 v76, v132, v76
	v_exp_f32_e32 v178, v74
	v_mul_f32_e32 v74, v75, v71
	v_exp_f32_e32 v188, v76
	v_mul_f32_e32 v76, v77, v73
	v_mul_f32_e32 v74, v131, v74
	v_mul_f32_e32 v76, v133, v76
	v_exp_f32_e32 v179, v74
	v_exp_f32_e32 v189, v76
	v_fma_f32 v74, -v178, v178, 1.0
	v_fma_f32 v76, -v188, v188, 1.0
	v_fma_f32 v75, -v179, v179, 1.0
	v_fma_f32 v77, -v189, v189, 1.0
	v_sqrt_f32_e32 v74, v74
	v_sqrt_f32_e32 v75, v75
	v_sqrt_f32_e32 v76, v76
	v_sqrt_f32_e32 v77, v77
	v_pk_mul_f32 v[50:51], v[50:51], v[70:71]
	v_pk_mul_f32 v[52:53], v[52:53], v[72:73]
	v_pk_mul_f32 v[180:181], v[50:51], v[74:75]
	v_pk_mul_f32 v[184:185], v[52:53], v[76:77]
	global_load_dwordx4 v[144:147], v[164:165], off
	global_load_dwordx4 v[140:143], v[162:163], off
	global_load_dwordx4 v[130:133], v[166:167], off
	v_lshl_add_u64 v[50:51], s[56:57], 0, v[150:151]
	v_lshl_add_u64 v[52:53], s[60:61], 0, v[150:151]
	v_lshl_add_u64 v[150:151], s[62:63], 0, v[150:151]
	global_load_dwordx4 v[126:129], v[50:51], off
	global_load_dwordx4 v[122:125], v[52:53], off
	global_load_dwordx4 v[86:89], v[150:151], off
	global_load_dwordx4 v[74:77], v[50:51], off
	global_load_dwordx4 v[70:73], v[52:53], off
	s_nop 0
	global_load_dwordx4 v[50:53], v[150:151], off
	v_lshlrev_b32_e32 v196, 16, v138
	v_and_b32_e32 v197, 0xffff0000, v138
	v_lshlrev_b32_e32 v200, 16, v134
	v_and_b32_e32 v201, 0xffff0000, v134
	v_lshlrev_b32_e32 v198, 16, v139
	v_and_b32_e32 v199, 0xffff0000, v139
	v_pk_mul_f32 v[138:139], v[96:97], v[196:197]
	v_lshlrev_b32_e32 v202, 16, v135
	v_and_b32_e32 v203, 0xffff0000, v135
	v_pk_mul_f32 v[134:135], v[168:169], v[200:201]
	v_lshlrev_b32_e32 v204, 16, v186
	v_and_b32_e32 v205, 0xffff0000, v186
	v_pk_mul_f32 v[162:163], v[136:137], v[198:199]
	v_pk_mul_f32 v[96:97], v[170:171], v[202:203]
	v_lshlrev_b32_e32 v206, 16, v187
	v_and_b32_e32 v207, 0xffff0000, v187
	v_pk_mul_f32 v[150:151], v[174:175], v[204:205]
	v_lshlrev_b32_e32 v208, 16, v190
	v_and_b32_e32 v209, 0xffff0000, v190
	v_pk_fma_f32 v[168:169], v[92:93], v[138:139], v[134:135]
	v_pk_mul_f32 v[174:175], v[92:93], v[158:159]
	v_pk_mul_f32 v[136:137], v[176:177], v[206:207]
	v_lshlrev_b32_e32 v210, 16, v191
	v_and_b32_e32 v211, 0xffff0000, v191
	v_pk_mul_f32 v[164:165], v[180:181], v[208:209]
	v_pk_fma_f32 v[166:167], v[172:173], v[168:169], v[150:151]
	v_pk_mul_f32 v[172:173], v[172:173], v[174:175]
	v_pk_fma_f32 v[180:181], v[148:149], v[162:163], v[96:97]
	v_pk_mul_f32 v[186:187], v[148:149], v[160:161]
	v_pk_mul_f32 v[176:177], v[184:185], v[210:211]
	v_pk_fma_f32 v[164:165], v[178:179], v[166:167], v[164:165]
	v_pk_mul_f32 v[170:171], v[178:179], v[172:173]
	v_pk_fma_f32 v[178:179], v[182:183], v[180:181], v[136:137]
	v_pk_mul_f32 v[184:185], v[182:183], v[186:187]
	v_pk_fma_f32 v[176:177], v[188:189], v[178:179], v[176:177]
	v_pk_mul_f32 v[182:183], v[188:189], v[184:185]
	v_mov_b32_e32 v92, v164
	v_mov_b32_e32 v93, v183
	v_mov_b32_e32 v96, v176
	v_mov_b32_e32 v97, v170
	v_mov_b32_e32 v148, v182
	v_mov_b32_e32 v137, v165
	v_mov_b32_e32 v151, v177
	v_mov_b32_e32 v136, v171
	s_nop 1
	v_fmac_f32_dpp v92, v92, v97 row_shr:1 row_mask:0xf bank_mask:0xf
	v_fmac_f32_dpp v137, v137, v136 row_shr:1 row_mask:0xf bank_mask:0xf
	v_fmac_f32_dpp v96, v96, v148 row_shr:1 row_mask:0xf bank_mask:0xf
	v_fmac_f32_dpp v151, v151, v93 row_shr:1 row_mask:0xf bank_mask:0xf
	v_mul_f32_dpp v97, v97, v97 row_shr:1 row_mask:0xf bank_mask:0xf
	v_mul_f32_dpp v136, v136, v136 row_shr:1 row_mask:0xf bank_mask:0xf
	v_mul_f32_dpp v148, v148, v148 row_shr:1 row_mask:0xf bank_mask:0xf
	v_mul_f32_dpp v93, v93, v93 row_shr:1 row_mask:0xf bank_mask:0xf
	v_fmac_f32_dpp v92, v92, v97 row_shr:2 row_mask:0xf bank_mask:0xf
	v_fmac_f32_dpp v137, v137, v136 row_shr:2 row_mask:0xf bank_mask:0xf
	v_fmac_f32_dpp v96, v96, v148 row_shr:2 row_mask:0xf bank_mask:0xf
	v_fmac_f32_dpp v151, v151, v93 row_shr:2 row_mask:0xf bank_mask:0xf
	v_mul_f32_dpp v97, v97, v97 row_shr:2 row_mask:0xf bank_mask:0xf
	v_mul_f32_dpp v136, v136, v136 row_shr:2 row_mask:0xf bank_mask:0xf
	v_mul_f32_dpp v148, v148, v148 row_shr:2 row_mask:0xf bank_mask:0xf
	v_mul_f32_dpp v93, v93, v93 row_shr:2 row_mask:0xf bank_mask:0xf
	v_fmac_f32_dpp v92, v92, v97 row_shr:4 row_mask:0xf bank_mask:0xf
	v_fmac_f32_dpp v137, v137, v136 row_shr:4 row_mask:0xf bank_mask:0xf
	v_fmac_f32_dpp v96, v96, v148 row_shr:4 row_mask:0xf bank_mask:0xf
	v_fmac_f32_dpp v151, v151, v93 row_shr:4 row_mask:0xf bank_mask:0xf
	v_mul_f32_dpp v97, v97, v97 row_shr:4 row_mask:0xf bank_mask:0xf
	v_mul_f32_dpp v136, v136, v136 row_shr:4 row_mask:0xf bank_mask:0xf
	v_mul_f32_dpp v148, v148, v148 row_shr:4 row_mask:0xf bank_mask:0xf
	v_mul_f32_dpp v93, v93, v93 row_shr:4 row_mask:0xf bank_mask:0xf
	v_fmac_f32_dpp v92, v92, v97 row_shr:8 row_mask:0xf bank_mask:0xf
	v_fmac_f32_dpp v137, v137, v136 row_shr:8 row_mask:0xf bank_mask:0xf
	v_fmac_f32_dpp v96, v96, v148 row_shr:8 row_mask:0xf bank_mask:0xf
	v_fmac_f32_dpp v151, v151, v93 row_shr:8 row_mask:0xf bank_mask:0xf
	v_mul_f32_dpp v97, v97, v97 row_shr:8 row_mask:0xf bank_mask:0xf
	v_mul_f32_dpp v136, v136, v136 row_shr:8 row_mask:0xf bank_mask:0xf
	v_mul_f32_dpp v148, v148, v148 row_shr:8 row_mask:0xf bank_mask:0xf
	v_mul_f32_dpp v93, v93, v93 row_shr:8 row_mask:0xf bank_mask:0xf
	s_nop 1
	v_mov_b32_e32 v188, 1.0
	v_mov_b32_e32 v189, 1.0
	v_mov_b32_e32 v192, 1.0
	v_mov_b32_e32 v193, 1.0
	v_mov_b32_dpp v188, v97 row_shr:1 row_mask:0xf bank_mask:0xf
	v_mov_b32_dpp v190, v92 row_shr:1 row_mask:0xf bank_mask:0xf bound_ctrl:1
	v_mov_b32_dpp v134, v97 row_newbcast:15 row_mask:0xf bank_mask:0xf bound_ctrl:1
	v_mov_b32_dpp v135, v92 row_newbcast:15 row_mask:0xf bank_mask:0xf bound_ctrl:1
	v_mov_b32_dpp v189, v136 row_shr:1 row_mask:0xf bank_mask:0xf
	v_mov_b32_dpp v191, v137 row_shr:1 row_mask:0xf bank_mask:0xf bound_ctrl:1
	v_mov_b32_dpp v136, v136 row_newbcast:15 row_mask:0xf bank_mask:0xf bound_ctrl:1
	v_mov_b32_dpp v137, v137 row_newbcast:15 row_mask:0xf bank_mask:0xf bound_ctrl:1
	v_mov_b32_dpp v192, v148 row_shr:1 row_mask:0xf bank_mask:0xf
	v_mov_b32_dpp v194, v96 row_shr:1 row_mask:0xf bank_mask:0xf bound_ctrl:1
	v_mov_b32_dpp v148, v148 row_newbcast:15 row_mask:0xf bank_mask:0xf bound_ctrl:1
	v_mov_b32_dpp v149, v96 row_newbcast:15 row_mask:0xf bank_mask:0xf bound_ctrl:1
	v_mov_b32_dpp v193, v93 row_shr:1 row_mask:0xf bank_mask:0xf
	v_mov_b32_dpp v195, v151 row_shr:1 row_mask:0xf bank_mask:0xf bound_ctrl:1
	v_mov_b32_dpp v150, v93 row_newbcast:15 row_mask:0xf bank_mask:0xf bound_ctrl:1
	v_mov_b32_dpp v151, v151 row_newbcast:15 row_mask:0xf bank_mask:0xf bound_ctrl:1
	v_cmp_eq_u32_e32 vcc, 0, v154
	s_and_saveexec_b64 s[14:15], vcc
	s_cbranch_execz .LBB0_865
	v_add_u32_e32 v92, s28, v230
	v_lshl_add_u32 v92, v92, 3, 0
	v_add_u32_e32 v92, 0x20200, v92
	ds_write_b128 v92, v[134:137]
	ds_write_b128 v92, v[148:151] offset:16
